# odd-vcu workgroups run the HGRN state scan after their attention units instead of before (memory-bound scan overlaps the other half's attention)
# speedup vs baseline: 1.0040x; 1.0040x over previous
.LBB0_1103:
	s_mov_b32 s32, 3
	s_cmp_lt_i32 s60, 6
	s_cselect_b64 s[0:1], -1, 0
	s_cmp_gt_i32 s61, 5
	s_cselect_b64 s[4:5], -1, 0
	s_and_b64 s[0:1], s[0:1], s[4:5]
	s_andn2_b64 vcc, exec, s[0:1]
	s_cbranch_vccnz .LBB0_1237
	s_bitcmp1_b32 s56, 0
	s_cbranch_scc0 .Lsc_scan
	s_mov_b32 s32, 0
	s_branch .Lsc_attn
.Lsc_scan:
	v_readlane_b32 s30, v253, 16
	s_cmpk_gt_i32 s56, 0xff
	v_readlane_b32 s31, v253, 17
	s_cbranch_scc1 .LBB0_1116
	v_lshlrev_b32_e32 v1, 2, v0
	s_waitcnt lgkmcnt(0)
	v_lshlrev_b32_e32 v3, 1, v0
	v_and_b32_e32 v2, 60, v1
	s_add_i32 s0, 0, 0x18800
	v_and_b32_e32 v151, 62, v3
	v_lshl_add_u32 v1, v2, 2, s0
	v_lshl_add_u32 v152, v151, 2, s0
	s_movk_i32 s0, 0x210
	v_or_b32_e32 v8, 0x600, v0
	v_cmp_gt_u32_e64 s[4:5], s0, v0
	v_or_b32_e32 v3, 0x200, v0
	s_movk_i32 s0, 0x810
	v_cndmask_b32_e64 v9, v0, v8, s[4:5]
	v_lshlrev_b32_e32 v10, 5, v9
	v_lshlrev_b32_e32 v9, 2, v9
	v_and_b32_e32 v22, 60, v9
	v_or_b32_e32 v9, 0x800, v0
	v_lshlrev_b32_e32 v4, 5, v3
	v_cmp_gt_u32_e64 s[6:7], s0, v9
	v_lshlrev_b32_e32 v3, 4, v3
	v_or_b32_e32 v5, 0x400, v0
	v_cndmask_b32_e64 v9, v0, v9, s[6:7]
	v_and_b32_e32 v3, 0x3f00, v3
	v_and_b32_e32 v20, 0xfe00, v10
	v_lshlrev_b32_e32 v10, 5, v9
	v_lshlrev_b32_e32 v9, 2, v9
	v_add_u32_e32 v154, v1, v3
	v_lshlrev_b32_e32 v3, 4, v5
	v_and_b32_e32 v16, 60, v9
	v_lshlrev_b32_e32 v9, 5, v0
	v_and_b32_e32 v3, 0x5f00, v3
	v_lshlrev_b32_e32 v6, 5, v5
	v_and_b32_e32 v18, 0x3e00, v9
	v_lshlrev_b32_e32 v9, 4, v0
	v_add_u32_e32 v155, v1, v3
	v_lshlrev_b32_e32 v3, 4, v8
	v_and_b32_e32 v4, 0x7e00, v4
	v_mov_b32_e32 v7, 0
	v_and_b32_e32 v6, 0xbe00, v6
	v_and_b32_e32 v14, 0x13e00, v10
	v_and_b32_e32 v9, 0x1f00, v9
	v_and_b32_e32 v3, 0x7f00, v3
	s_mov_b32 s8, 0xfffe0000
	s_mov_b32 s1, 0
	v_lshrrev_b32_e32 v150, 5, v0
	v_add_u32_e32 v153, v1, v9
	v_add_u32_e32 v156, v1, v3
	s_lshl_b32 s22, s56, 2
	s_lshl_b32 s23, s3, 2
	s_lshl_b32 s24, s56, 6
	s_lshl_b32 s25, s3, 6
	s_mov_b32 s26, 0x182c00
	v_lshlrev_b32_e32 v8, 2, v4
	v_mov_b32_e32 v9, v7
	v_lshlrev_b32_e32 v10, 2, v2
	v_mov_b32_e32 v11, v7
	v_lshlrev_b32_e32 v12, 2, v6
	v_mov_b32_e32 v13, v7
	v_lshlrev_b32_e32 v14, 2, v14
	v_mov_b32_e32 v15, v7
	v_lshlrev_b32_e32 v16, 2, v16
	v_mov_b32_e32 v17, v7
	v_lshlrev_b32_e32 v18, 2, v18
	v_mov_b32_e32 v19, v7
	v_lshlrev_b32_e32 v20, 2, v20
	v_lshlrev_b32_e32 v22, 2, v22
	s_mov_b32 s9, -1
	s_mov_b32 s27, 0xfffe0000
	v_mov_b32_e32 v157, 0x820000
	v_mov_b32_e32 v158, 0xc20000
	v_mov_b32_e32 v159, 0xfe0000
	s_mov_b32 s28, s56
	s_branch .LBB0_1107

.LBB0_1116:
	s_cmp_eq_u32 s32, 2
	s_cbranch_scc1 .Lsc_s5

.LBB0_1181:
	s_cmp_eq_u32 s32, 0
	s_cbranch_scc0 .Lsc_s5
	s_mov_b32 s32, 2
	s_waitcnt lgkmcnt(0)
	s_barrier
	s_branch .Lsc_scan
